# attention unit head: the wait before the first QK MFMA no longer drains the just-issued tile-2 DMAs (vmcnt(2) instead of vmcnt(0)); the loop's own counted wait retires them
# speedup vs baseline: 1.0080x; 1.0043x over previous
; #define LAS __attribute__((address_space(3)))
; __device__ __forceinline__ int v_rd_base(int lane) { return (((lane & 3) << 3) | (((lane >> 2) & 3) << 6) | (((lane >> 4) & 1) << 5)) + ((lane >> 5) & 1) * 1024; }
; #define DMA(t) do { const int t_ = (t) < NT ? (t) : NT - 1; const long off_ = (long)t_ * (KVBLK * LDK); \
;         __builtin_amdgcn_global_load_lds((const unsigned*)(kptr + off_), (LAS unsigned*)(ldsK + SLOT(t)), 16, 0, 0); \
;         __builtin_amdgcn_global_load_lds((const unsigned*)(vptr + off_), (LAS unsigned*)(ldsV + SLOT(t)), 16, 0, 0); } while (0)
; #define WBAR(N) asm volatile("s_waitcnt vmcnt(" #N ") lgkmcnt(0)\n\ts_barrier" ::: "memory")
; __device__ __forceinline__ void attn_body(const bf16* __restrict__ Qb, const bf16* __restrict__ Kh, const bf16* __restrict__ Vh, bf16* __restrict__ Ob, int seq, float m0l2, char* lds, bool pre, bool post) {
;     ...
;     const int oo = (wsg * 64 + lane) * 16;
;     const int ksr = oo >> 8, kcolB = (oo & 255) ^ ((ksr & 15) << 4);
;     const bf16* kptr = Kh + (long)(ksr + 32 * (kcolB >> 7)) * LDK + ((kcolB & 127) >> 1);
;     const int vkk = ((oo >> 9) >> 1) * 8 + ((oo & 511) >> 6), vcc = ((oo >> 9) & 1) * 32 + ((oo & 63) >> 1);
;     const bf16* vptr = Vh + (long)((vkk & ~0xC) | ((vkk & 4) << 1) | ((vkk & 8) >> 1)) * LDK + vcc;
;     LAS unsigned char* const ldsK = (LAS unsigned char*)lds + OFF_K + wsg * 1024; LAS unsigned char* const ldsV = (LAS unsigned char*)lds + OFF_V + wsg * 1024;
;     const int vb0 = (int)(uintptr_t)V_lds + v_rd_base(lane);
;     const int NT = seq / KVBLK;
;     ...
;     if (!pre) { DMA(0); DMA(1); } DMA(2); WBAR(2);
;     qkt(pA0, pA1, K_lds, qr, negm, r32, hi); partialSM(pA0);
;     int j = 1;
.LBB0_26:
	s_lshl_b32 s25, s7, 6
	s_cmp_lg_u32 0, -1
	s_cselect_b32 s39, 0, 0
	v_lshl_add_u64 v[16:17], v[132:133], 0, s[82:83]
	s_add_i32 m0, s26, 0xc000
	v_lshlrev_b32_e32 v39, 8, v150
	global_load_lds_dwordx4 v[16:17], off
	v_lshl_add_u64 v[16:17], v[134:135], 0, s[82:83]
	s_add_i32 m0, s26, 0x4000
	s_movk_i32 s7, 0xc0
	global_load_lds_dwordx4 v[16:17], off
	v_lshlrev_b32_e32 v16, 4, v150
	v_and_b32_e32 v80, 0xf0, v16
	v_lshrrev_b32_e32 v39, 4, v150
	v_lshlrev_b32_e32 v39, 11, v39
	v_lshl_add_u32 v39, v130, 4, v39
	v_add_u32_e32 v39, v39, v80
	v_mov_b32_e32 v163, v39
	s_waitcnt vmcnt(2) lgkmcnt(0)
	s_barrier
	v_add_u32_e32 v154, 0, v163
	ds_read_b128 v[40:43], v154 offset:32768
	v_or_b32_e32 v16, 0x80, v130
	v_add_u32_e32 v164, 4096, v39
	v_add_u32_e32 v162, 0, v164
	ds_read_b128 v[44:47], v162 offset:32768
	s_waitcnt vmcnt(2) lgkmcnt(0)
	v_mfma_f32_32x32x16_bf16 v[16:31], v[40:43], v[124:127], v[48:63]
	v_or_b32_e32 v40, 32, v130
	v_add_u32_e32 v165, 512, v39
	v_add_u32_e32 v153, 0, v165
	ds_read_b128 v[40:43], v153 offset:32768
	s_add_i32 s38, s38, s37
	v_mfma_f32_32x32x16_bf16 v[64:79], v[44:47], v[124:127], v[48:63]
	v_or_b32_e32 v44, 0xa0, v130
	v_add_u32_e32 v166, 4608, v39
	v_add_u32_e32 v157, 0, v166
	ds_read_b128 v[44:47], v157 offset:32768
	s_waitcnt lgkmcnt(1)
	v_mfma_f32_32x32x16_bf16 v[16:31], v[40:43], v[120:123], v[16:31]
	v_or_b32_e32 v40, 64, v130
	v_add_u32_e32 v167, 1024, v39
	v_add_u32_e32 v156, 0, v167
	ds_read_b128 v[40:43], v156 offset:32768
	s_waitcnt lgkmcnt(1)
	v_mfma_f32_32x32x16_bf16 v[64:79], v[44:47], v[120:123], v[64:79]
	v_or_b32_e32 v44, 0xc0, v130
	v_add_u32_e32 v168, 5120, v39
	v_add_u32_e32 v158, 0, v168
	ds_read_b128 v[44:47], v158 offset:32768
	s_waitcnt lgkmcnt(1)
	v_mfma_f32_32x32x16_bf16 v[16:31], v[40:43], v[116:119], v[16:31]
	v_or_b32_e32 v40, 0x60, v130
	v_add_u32_e32 v169, 1536, v39
	v_add_u32_e32 v155, 0, v169
	ds_read_b128 v[40:43], v155 offset:32768
	s_waitcnt lgkmcnt(1)
	v_mfma_f32_32x32x16_bf16 v[64:79], v[44:47], v[116:119], v[64:79]
	v_or_b32_e32 v44, 0xe0, v130
	v_add_u32_e32 v170, 5632, v39
	v_add_u32_e32 v159, 0, v170
	ds_read_b128 v[44:47], v159 offset:32768
	v_lshlrev_b32_e32 v39, 1, v131
	v_and_b32_e32 v39, 32, v39
	v_and_or_b32 v38, v38, s7, v39
	s_waitcnt lgkmcnt(1)
	v_mfma_f32_32x32x16_bf16 v[16:31], v[40:43], v[112:115], v[16:31]
	v_lshlrev_b32_e32 v39, 5, v131
	v_and_b32_e32 v39, 0x400, v39
	v_or3_b32 v129, v38, v39, v35
	v_add_u32_e32 v172, s39, v129
	s_mov_b32 s7, -1
	s_nop 6
	v_exp_f32_e32 v183, v16
	s_waitcnt lgkmcnt(0)
	v_mfma_f32_32x32x16_bf16 v[64:79], v[44:47], v[112:115], v[64:79]
	v_exp_f32_e32 v188, v17
	v_mad_u64_u32 v[16:17], s[46:47], s27, v211, v[32:33]
	v_lshl_add_u64 v[16:17], v[16:17], 0, v[160:161]
	v_lshl_add_u64 v[140:141], s[28:29], 0, v[16:17]
	v_add3_u32 v16, s38, v37, v36
	v_ashrrev_i32_e32 v17, 31, v16
	v_exp_f32_e32 v185, v18
	v_exp_f32_e32 v187, v19
	v_exp_f32_e32 v184, v20
	v_exp_f32_e32 v186, v21
	v_exp_f32_e32 v181, v22
	v_exp_f32_e32 v182, v23
	v_exp_f32_e32 v178, v24
	v_exp_f32_e32 v180, v25
	v_exp_f32_e32 v176, v26
	v_exp_f32_e32 v179, v27
	v_exp_f32_e32 v175, v28
	v_exp_f32_e32 v177, v29
	v_exp_f32_e32 v173, v30
	v_exp_f32_e32 v174, v31
	v_lshlrev_b64 v[16:17], 8, v[16:17]
	v_mad_u64_u32 v[16:17], s[38:39], s27, v211, v[16:17]
	v_add_u32_e32 v18, v34, v35
	v_lshl_or_b32 v16, v18, 1, v16
	v_mov_b32_e32 v160, 0
	v_lshl_add_u64 v[142:143], s[28:29], 0, v[16:17]
	s_mov_b32 s27, 0x8000
	v_mov_b32_e32 v16, 0
	v_mov_b32_e32 v17, v160
	v_mov_b32_e32 v18, v160
	v_mov_b32_e32 v19, v160
	v_mov_b32_e32 v20, v160
	v_mov_b32_e32 v21, v160
	v_mov_b32_e32 v22, v160
	v_mov_b32_e32 v23, v160
	v_mov_b32_e32 v24, v160
	v_mov_b32_e32 v25, v160
	v_mov_b32_e32 v26, v160
	v_mov_b32_e32 v27, v160
	v_mov_b32_e32 v28, v160
	v_mov_b32_e32 v29, v160
	v_mov_b32_e32 v30, v160
	v_mov_b32_e32 v31, v160
	v_mov_b32_e32 v32, 0
	v_mov_b32_e32 v33, v160
	v_mov_b32_e32 v34, v160
	v_mov_b32_e32 v35, v160
	v_mov_b32_e32 v36, v160
	v_mov_b32_e32 v37, v160
	v_mov_b32_e32 v38, v160
	v_mov_b32_e32 v39, v160
	v_mov_b32_e32 v40, v160
	v_mov_b32_e32 v41, v160
	v_mov_b32_e32 v42, v160
	v_mov_b32_e32 v43, v160
	v_mov_b32_e32 v44, v160
	v_mov_b32_e32 v45, v160
	v_mov_b32_e32 v46, v160
	v_mov_b32_e32 v47, v160
	v_lshl_add_u64 v[140:141], v[140:141], 0, s[72:73]
	v_lshl_add_u64 v[142:143], v[142:143], 0, s[72:73]
	s_mov_b64 s[38:39], 0x10e06000
	s_mov_b64 s[46:47], 0x11686000
	v_lshl_add_u64 v[140:141], v[140:141], 0, s[38:39]
	v_lshl_add_u64 v[142:143], v[142:143], 0, s[46:47]
	s_nop 0
	v_readfirstlane_b32 s50, v140
	v_readfirstlane_b32 s51, v141
	v_readfirstlane_b32 s52, v142
	v_readfirstlane_b32 s53, v143
	s_sub_u32 s50, s50, 0x10000
	s_subb_u32 s51, s51, 0
	s_sub_u32 s52, s52, 0x10000
	s_subb_u32 s53, s53, 0
	v_subrev_u32_e32 v140, s50, v140
	v_subrev_u32_e32 v142, s52, v142
	ds_read_b128 v[234:237], v163 offset:40960
	ds_read_b128 v[238:241], v165 offset:40960
	ds_read_b128 v[242:245], v167 offset:40960
	ds_read_b128 v[246:249], v169 offset:40960
	v_readfirstlane_b32 s37, v151
	s_nop 0
	s_cmp_ge_u32 s37, 4
	s_cbranch_scc0 .Lattn_prio_skip
	s_setprio 1
